# group barriers in flag form: one L2-resident flag per workgroup on a shared 128-byte line, polled by 32 lanes; no counter round trip
# speedup vs baseline: 1.0038x; 1.0038x over previous
; #define LAS __attribute__((address_space(3)))
; __device__ __forceinline__ unsigned xb_add(unsigned* p, unsigned v) { return __hip_atomic_fetch_add(p, v, __ATOMIC_RELAXED, __HIP_MEMORY_SCOPE_AGENT); }
; __device__ __forceinline__ unsigned xb_xcc_id() { return (unsigned)__builtin_amdgcn_s_getreg((3 << 11) | 20) & 0xFu; }
; __device__ __forceinline__ XcdBarrier xcd_barrier_post(unsigned* bar, volatile LAS unsigned* st) {
;     XcdBarrier b; b.bar = bar; b.x = xb_xcc_id(); b.st = st;
;     if (threadIdx.x == 0) (void)xb_add(&bar[XB_XCNT(b.x)], 1u);
;     return b;
; __global__ void __launch_bounds__(NWAVES * 64, 2) skel_fwd(Args args) {
;     ...
;     unsigned char* ws = args.ws;
;     F.ctl = (gu32*)(ws + WS_CTL);
;     F.x = args.in[0]; F.g_pre_mix = args.in[1]; F.w_in = args.in[2]; F.w_pa = args.in[15]; F.w_pb = args.in[16]; F.w_o = args.in[17];
;     F.g_post_mix = args.in[18]; F.g_pre_mlp = args.in[19]; F.w_up = args.in[20]; F.w_down = args.in[21]; F.g_post_mlp = args.in[22]; F.out = args.out;
;     F.w_if = args.in[11]; F.w_q_ml = args.in[8]; F.w_k_ml = args.in[9]; F.w_v_ml = args.in[10]; F.Wif_t = (bf16*)(ws + WS_WIF);
;     F.W1t = (bf16*)(ws + WS_W1); F.Wpa_t = (bf16*)(ws + WS_WPA); F.Wpb_t = (bf16*)(ws + WS_WPB); F.Wo_t = (bf16*)(ws + WS_WO); F.Wup_t = (bf16*)(ws + WS_WUP); F.Wdn_t = (bf16*)(ws + WS_WDN);
;     F.XN = (bf16*)args.out + (size_t)M * 1024; F.XS = (float*)(ws + WS_SMALL + 1024 * 1024);
;     F.PROJ = (bf16*)(ws + WS_PROJ); F.A_a = (bf16*)(ws + WS_A); F.A_b = F.A_a + 512;
;     F.MERGED = (bf16*)(ws + WS_R1); F.XN2 = (bf16*)(ws + WS_XN2); F.U = (bf16*)(ws + WS_U);
;     for (int u = F.tid; u < (LDS_BYTES - LDSCTL_OFF) / 4; u += NWAVES * 64) ((LAS unsigned*)(F.lds + LDSCTL_OFF))[u] = 0u;
;     __syncthreads();
;     XcdBarrier bar = xcd_barrier_post((unsigned*)(F.ctl + CW_BAR), F.MISC + 8);
.LBB0_3:
	s_or_b64 exec, exec, s[2:3]
	s_load_dwordx16 s[52:67], s[0:1], 0x0
	s_load_dwordx16 s[8:23], s[0:1], 0x40
	s_waitcnt lgkmcnt(0)
	s_barrier
	s_add_u32 s86, s88, 0x4000
	v_writelane_b32 v241, s8, 2
	s_addc_u32 s87, s89, 0
	v_cmp_eq_u32_e64 s[2:3], 0, v0
	v_writelane_b32 v241, s9, 3
	v_writelane_b32 v241, s10, 4
	v_writelane_b32 v241, s11, 5
	v_writelane_b32 v241, s12, 6
	v_writelane_b32 v241, s13, 7
	v_writelane_b32 v241, s14, 8
	v_writelane_b32 v241, s15, 9
	v_writelane_b32 v241, s16, 10
	v_writelane_b32 v241, s17, 11
	v_writelane_b32 v241, s18, 12
	v_writelane_b32 v241, s19, 13
	v_writelane_b32 v241, s20, 14
	v_writelane_b32 v241, s21, 15
	v_writelane_b32 v241, s22, 16
	v_writelane_b32 v241, s23, 17
	s_load_dwordx16 s[8:23], s[0:1], 0x80
	s_getreg_b32 s0, hwreg(HW_REG_XCC_ID, 0, 4)
	s_and_b32 s97, s0, 15
	s_waitcnt lgkmcnt(0)
	s_and_b32 s99, s96, 7
	s_lshl_b32 s101, s99, 6
	s_lshl_b32 s99, s99, 7
	s_add_i32 s99, s99, 0x42000
	s_lshr_b32 s98, s96, 3
	s_lshl_b32 s98, s98, 2
	s_add_i32 s98, s98, s99
	s_lshl_b32 s100, s97, 2
	s_or_b32 s101, s101, s100
	s_add_i32 s101, s101, 0x41000
	v_writelane_b32 v241, s8, 18
	s_nop 1
	v_writelane_b32 v241, s9, 19
	v_writelane_b32 v241, s10, 20
	v_writelane_b32 v241, s11, 21
	v_writelane_b32 v241, s12, 22
	v_writelane_b32 v241, s13, 23
	v_writelane_b32 v241, s14, 24
	v_writelane_b32 v241, s15, 25
	v_writelane_b32 v241, s16, 26
	v_writelane_b32 v241, s17, 27
	v_writelane_b32 v241, s18, 28
	v_writelane_b32 v241, s19, 29
	v_writelane_b32 v241, s20, 30
	v_writelane_b32 v241, s21, 31
	v_writelane_b32 v241, s22, 32
	v_writelane_b32 v241, s23, 33
	s_mov_b64 s[0:1], exec
	v_writelane_b32 v241, s2, 34
	s_nop 1
	v_writelane_b32 v241, s3, 35
	s_and_b64 s[2:3], s[0:1], s[2:3]
	s_mov_b64 exec, s[2:3]
	s_cbranch_execz .LBB0_6
	s_mov_b64 s[2:3], exec
	v_mbcnt_lo_u32_b32 v1, s2, 0
	v_mbcnt_hi_u32_b32 v1, s3, v1
	v_cmp_eq_u32_e32 vcc, 0, v1
	s_and_b64 s[6:7], exec, vcc
	s_mov_b64 exec, s[6:7]
	s_cbranch_execz .LBB0_6
	s_lshl_b32 s5, s97, 8
	s_bcnt1_i32_b64 s2, s[2:3]
	v_mov_b32_e32 v1, s5
	v_mov_b32_e32 v2, s2
	global_atomic_add v1, v2, s[86:87] offset:1024
	v_mov_b32_e32 v3, s101
	v_mov_b32_e32 v4, 1
	global_atomic_add v3, v4, s[88:89]

;     __host__ __device__ bool next(int i, Unit& u) const {
;         const long L = (long)i * G + c; if (L >= nwg) return false;
;         int wgid = (int)L; { const int q = nwg / NXCD, r = nwg % NXCD, xcd = wgid % NXCD, off = wgid / NXCD; wgid = (xcd < r ? xcd * (q + 1) : r * (q + 1) + (xcd - r) * q) + off; }
;         const int nig = wgm * nN, gid = wgid / nig, fm = gid * wgm, gsz = (nM - fm) < wgm ? (nM - fm) : wgm;
;         u.pm = fm + ((wgid % nig) % gsz); u.pn = (wgid % nig) / gsz; return true;
; template <class Epi, class Sched, bool ALIGN_EPI = false, bool SP2 = false>
; __device__ __forceinline__ void gemm_phase(PG8_LAS unsigned char* lds, const Gemm g, const Sched& S, const Epi& E) {
;     ...
;     if (!S.next(0, cur)) return;
.LBB0_181:
	s_or_b64 exec, exec, s[0:1]
	v_mov_b32_e32 v10, v0
	s_cmpk_lt_i32 s96, 0x4c0
	s_waitcnt lgkmcnt(0)
	s_barrier
	v_mov_b32_e32 v1, s101
	global_load_dword v1, v1, s[88:89] sc1
	s_waitcnt vmcnt(0)
	v_cmp_ne_u32_e32 vcc, 32, v1
	s_nop 1
	v_cndmask_b32_e64 v1, 0, 1, vcc
	v_or_b32_e32 v1, s98, v1
	s_nop 0
	v_readfirstlane_b32 s98, v1
	s_cselect_b64 s[0:1], -1, 0
	s_cmpk_gt_i32 s96, 0x4bf
	v_readfirstlane_b32 s2, v10
	s_cbranch_scc1 .LBB0_183
	s_ashr_i32 s3, s96, 31
	s_lshr_b32 s3, s3, 29
	s_add_i32 s3, s96, s3
	s_ashr_i32 s4, s3, 3
	s_and_b32 s3, s3, -8
	s_sub_i32 s3, s96, s3
	s_cmp_lt_i32 s3, 0
	s_movk_i32 s5, 0x99
	s_cselect_b32 s5, s5, 0x98
	s_mul_i32 s3, s5, s3
	s_add_i32 s3, s3, s4
	s_mul_hi_i32 s4, s3, 0x6bca1af3
	s_lshr_b32 s5, s4, 31
	s_ashr_i32 s4, s4, 4
	s_add_i32 s4, s4, s5
	s_lshl_b32 s5, s4, 1
	s_mul_i32 s4, s4, 38
	s_sub_i32 s3, s3, s4
	s_bfe_u32 s4, s3, 0x10007
	s_add_i32 s4, s3, s4
	s_bfe_i32 s6, s4, 0x80000
	s_and_b32 s4, s4, 0xfe
	s_sub_i32 s3, s3, s4
	s_sext_i32_i16 s6, s6
	s_sext_i32_i8 s3, s3
	s_add_i32 s18, s5, s3
	s_ashr_i32 s4, s6, 1

; __device__ __forceinline__ unsigned xb_ld(unsigned* p)              { return __hip_atomic_load(p, __ATOMIC_RELAXED, __HIP_MEMORY_SCOPE_AGENT); }
; __device__ __forceinline__ unsigned xb_add(unsigned* p, unsigned v) { return __hip_atomic_fetch_add(p, v, __ATOMIC_RELAXED, __HIP_MEMORY_SCOPE_AGENT); }
; #define XB_SPIN(cond, bar) do { unsigned _sp = 0; while (cond) { __builtin_amdgcn_s_sleep(1); \
;     if ((++_sp & 255u) == 0u) { if (xb_ld(&(bar)[XB_TMO])) break; if (_sp > XB_SPIN_CAP) { atomicAdd(&(bar)[XB_TMO], 1u); break; } } } } while (0)
; __device__ __forceinline__ void xcd_barrier(const XcdBarrier& b) {
;     asm volatile("s_waitcnt vmcnt(0)" ::: "memory");
;     __syncthreads();
;     if (threadIdx.x == 0) {
;         unsigned* bar = b.bar;
;         __builtin_amdgcn_s_waitcnt(0);
;         unsigned nloc = b.st[0], nx = b.st[1];
;         if (nloc == 0u) { xcd_barrier_complete(bar, b.x, nloc, nx); b.st[0] = nloc; b.st[1] = nx; }
;         const unsigned old = xb_add(&bar[XB_XSUB(b.x)], 1u);
;         const unsigned gen = old / nloc;
;         asm volatile("buffer_inv sc1" ::: "memory");
;         if (old + 1u == (gen + 1u) * nloc) {
;             __builtin_amdgcn_fence(__ATOMIC_RELEASE, "agent");
;             asm volatile("s_waitcnt vmcnt(0)" ::: "memory");
;             const unsigned og = xb_add(&bar[XB_TOP], 1u);
;             const unsigned tg = og / nx;
;             if (og + 1u == (tg + 1u) * nx) xb_add(&bar[XB_TOPGEN], 1u);
;             else XB_SPIN(xb_ld(&bar[XB_TOPGEN]) == tg, bar);
;             asm volatile("" ::: "memory");
;             xb_add(&bar[XB_XGEN(b.x)], 1u);
;             asm volatile("s_waitcnt vmcnt(0)" ::: "memory");
;         } else {
;             XB_SPIN(xb_ld(&bar[XB_XGEN(b.x)]) == gen, bar);
;             asm volatile("" ::: "memory");
;             asm volatile("s_waitcnt vmcnt(0)" ::: "memory");
;         }
;     }
;     __syncthreads();
.LBB0_233:
	s_waitcnt vmcnt(0)
	s_waitcnt vmcnt(0)
	s_barrier
	s_mov_b64 s[0:1], exec
	v_readlane_b32 s2, v241, 34
	v_readlane_b32 s3, v241, 35
	s_and_b64 s[2:3], s[0:1], s[2:3]
	v_writelane_b32 v241, s94, 55
	s_nop 1
	v_writelane_b32 v241, s95, 56
	s_mov_b64 exec, s[2:3]
	s_cbranch_execz .LBB0_289
	s_waitcnt vmcnt(0) lgkmcnt(0)
	s_and_b32 s100, s98, -4
	v_mov_b32_e32 v1, s100
	v_mov_b32_e32 v2, 1
	s_bitcmp0_b32 s98, 0
	s_cbranch_scc1 .Lgb_co1
	buffer_wbl2 sc1
	s_waitcnt vmcnt(0)
	global_store_dword v1, v2, s[88:89] offset:1024 sc1
	s_branch .Lgb_inv1
.Lgb_co1:
	global_store_dword v1, v2, s[88:89] offset:1024
.Lgb_inv1:
	buffer_inv sc1
	s_mov_b32 exec_lo, -1
	s_mov_b32 exec_hi, 0
	v_mbcnt_lo_u32_b32 v3, -1, 0
	v_lshl_add_u32 v3, v3, 2, s99
	s_mov_b32 s100, 0
.Lgb_spin1:
	global_load_dword v4, v3, s[88:89] offset:1024 sc1
	s_waitcnt vmcnt(0)
	v_cmp_ne_u32_e32 vcc, 0, v4
	s_cmp_eq_u32 vcc_lo, -1
	s_cbranch_scc1 .Lgb_done1
	s_sleep 1
	s_add_i32 s100, s100, 1
	s_cmp_lt_u32 s100, 0x40000
	s_cbranch_scc1 .Lgb_spin1
.Lgb_done1:
	s_branch .LBB0_289
	s_add_i32 s2, 0, 0x27f60
	v_mov_b32_e32 v1, s2
	s_waitcnt vmcnt(0) expcnt(0) lgkmcnt(0)
	ds_read_b32 v3, v1
	s_add_i32 s2, 0, 0x27f64
	v_mov_b32_e32 v1, s2
	ds_read_b32 v1, v1
	s_waitcnt lgkmcnt(1)
	v_cmp_ne_u32_e32 vcc, 0, v3
	s_cbranch_vccnz .LBB0_252
	v_readlane_b32 s2, v241, 0
	v_readlane_b32 s3, v241, 1
	s_load_dwordx2 s[6:7], s[2:3], 0x4
	s_add_u32 s2, s88, 0x4200
	s_addc_u32 s3, s89, 0
	s_add_u32 s4, s88, 0x4400
	s_addc_u32 s5, s89, 0
	s_waitcnt lgkmcnt(0)
	s_mul_i32 s30, s6, s93
	s_add_u32 s6, s88, 0x4500
	s_mul_i32 s30, s30, s7
	s_addc_u32 s7, s89, 0
	s_add_u32 s8, s88, 0x4600
	s_addc_u32 s9, s89, 0
	s_add_u32 s10, s88, 0x4700
	s_addc_u32 s11, s89, 0
	s_add_u32 s12, s88, 0x4800
	s_addc_u32 s13, s89, 0
	s_add_u32 s14, s88, 0x4900
	s_addc_u32 s15, s89, 0
	s_add_u32 s16, s88, 0x4a00
	s_addc_u32 s17, s89, 0
	s_add_u32 s18, s88, 0x4b00
	s_addc_u32 s19, s89, 0
	s_add_u32 s20, s88, 0x4c00
	s_addc_u32 s21, s89, 0
	s_add_u32 s22, s88, 0x4d00
	s_addc_u32 s23, s89, 0
	s_add_u32 s24, s88, 0x4e00
	s_addc_u32 s25, s89, 0
	s_add_u32 s26, s88, 0x4f00
	s_addc_u32 s27, s89, 0
	s_add_u32 s28, s88, 0x5000
	s_addc_u32 s29, s89, 0
	s_add_u32 s34, s88, 0x5100
	s_addc_u32 s35, s89, 0
	s_add_u32 s74, s88, 0x5200
	s_addc_u32 s75, s89, 0
	s_add_u32 s84, s88, 0x5300
	s_mov_b64 s[36:37], s[86:87]
	s_addc_u32 s85, s89, 0
	s_mov_b32 s31, 1
	v_mov_b32_e32 v17, 0
	s_branch .LBB0_237

; __device__ __forceinline__ unsigned xb_ld(unsigned* p)              { return __hip_atomic_load(p, __ATOMIC_RELAXED, __HIP_MEMORY_SCOPE_AGENT); }
; __device__ __forceinline__ unsigned xb_add(unsigned* p, unsigned v) { return __hip_atomic_fetch_add(p, v, __ATOMIC_RELAXED, __HIP_MEMORY_SCOPE_AGENT); }
; #define XB_SPIN(cond, bar) do { unsigned _sp = 0; while (cond) { __builtin_amdgcn_s_sleep(1); \
;     if ((++_sp & 255u) == 0u) { if (xb_ld(&(bar)[XB_TMO])) break; if (_sp > XB_SPIN_CAP) { atomicAdd(&(bar)[XB_TMO], 1u); break; } } } } while (0)
; __device__ __forceinline__ void xcd_barrier(const XcdBarrier& b) {
;     asm volatile("s_waitcnt vmcnt(0)" ::: "memory");
;     __syncthreads();
;     if (threadIdx.x == 0) {
;         unsigned* bar = b.bar;
;         __builtin_amdgcn_s_waitcnt(0);
;         unsigned nloc = b.st[0], nx = b.st[1];
;         if (nloc == 0u) { xcd_barrier_complete(bar, b.x, nloc, nx); b.st[0] = nloc; b.st[1] = nx; }
;         const unsigned old = xb_add(&bar[XB_XSUB(b.x)], 1u);
;         const unsigned gen = old / nloc;
;         asm volatile("buffer_inv sc1" ::: "memory");
;         if (old + 1u == (gen + 1u) * nloc) {
;             __builtin_amdgcn_fence(__ATOMIC_RELEASE, "agent");
;             asm volatile("s_waitcnt vmcnt(0)" ::: "memory");
;             const unsigned og = xb_add(&bar[XB_TOP], 1u);
;             const unsigned tg = og / nx;
;             if (og + 1u == (tg + 1u) * nx) xb_add(&bar[XB_TOPGEN], 1u);
;             else XB_SPIN(xb_ld(&bar[XB_TOPGEN]) == tg, bar);
;             asm volatile("" ::: "memory");
;             xb_add(&bar[XB_XGEN(b.x)], 1u);
;             asm volatile("s_waitcnt vmcnt(0)" ::: "memory");
;         } else {
;             XB_SPIN(xb_ld(&bar[XB_XGEN(b.x)]) == gen, bar);
;             asm volatile("" ::: "memory");
;             asm volatile("s_waitcnt vmcnt(0)" ::: "memory");
;         }
;     }
;     __syncthreads();
.LBB0_309:
	s_waitcnt vmcnt(0)
	s_barrier
	s_mov_b64 s[2:3], exec
	v_readlane_b32 s4, v241, 34
	v_readlane_b32 s5, v241, 35
	s_and_b64 s[4:5], s[2:3], s[4:5]
	s_mov_b64 exec, s[4:5]
	s_cbranch_execz .LBB0_361
	s_waitcnt vmcnt(0) lgkmcnt(0)
	s_and_b32 s100, s98, -4
	v_mov_b32_e32 v1, s100
	v_mov_b32_e32 v2, 1
	s_bitcmp0_b32 s98, 0
	s_cbranch_scc1 .Lgb_co2
	buffer_wbl2 sc1
	s_waitcnt vmcnt(0)
	global_store_dword v1, v2, s[88:89] offset:2048 sc1
	s_branch .Lgb_inv2
.Lgb_co2:
	global_store_dword v1, v2, s[88:89] offset:2048

; template <int PH> __device__ __forceinline__ void run_phase(Frame& F, const Args& args) {
;     ...
;         mix::MixBufs MB;
;         MB.PROJ = F.PROJ;
;         MB.Eg = (bf16*)(ws + WS_R1);
;         MB.xcm = (bf16*)F.out; MB.vm = MB.xcm + (size_t)M * 512;
;         MB.dlast = (float*)(ws + WS_SMALL); MB.li = (float*)(ws + WS_SMALL + 256 * 1024); MB.fcum = (float*)(ws + WS_SMALL + 512 * 1024); MB.wgt = (float*)(ws + WS_SMALL + 1536 * 1024);
;         MB.flast = (float*)(ws + WS_SMALL + 768 * 1024); MB.mloc = (float*)(ws + WS_SMALL + 772 * 1024);
;         MB.WcmT = F.Wif_t; MB.Lg = (float*)(ws + WS_GSEG); MB.Lm = (float*)(ws + WS_W1); MB.nL = (float*)(ws + WS_W1 + 8 * MiB);
;         MB.A_a = F.A_a; MB.A_b = F.A_b;
;         MB.w_a_up = args.in[3]; MB.b_a_up = args.in[4]; MB.g_gla_norm = args.in[5]; MB.conv_w = args.in[6]; MB.conv_b = args.in[7]; MB.w_q = args.in[8]; MB.w_k = args.in[9]; MB.w_v = args.in[10];
;         MB.b_if = args.in[12]; MB.ml_skip = args.in[13]; MB.g_ml_norm = args.in[14];
;         if (IN(2)) {
;             for (int u = F.vcu; u < BATCH * NCH; u += F.G) mix::prep_unit(F.lds, MB, u >> 5, u & 31, F.tid);
;         }
;         if (IN(3)) {
;             if (F.G == 256) { const int l = F.vcu & 31, xc = F.vcu >> 5;
;                 if (l < 24) { const int ty = l >= 12, r = xc * 12 + (l - 12 * ty), b = r / 12, h = (r % 12) / 3, sg = r % 3;
;                     if (ty == 0) mix::gla_unit<false>(F.lds, MB, b, h, sg, F.tid); else mix::ml_loc_unit(F.lds, MB, b, h, sg, F.tid); } }
;             else
;             for (int u = F.vcu; u < 192; u += F.G) { const int ty = u / 96, r = u % 96, b = r / 12, h = (r % 12) / 3, sg = r % 3;
;                 if (ty == 0) mix::gla_unit<false>(F.lds, MB, b, h, sg, F.tid); else mix::ml_loc_unit(F.lds, MB, b, h, sg, F.tid); }
.Lgb_spin2:
	global_load_dword v4, v3, s[88:89] offset:2048 sc1
	s_waitcnt vmcnt(0)
	v_cmp_ne_u32_e32 vcc, 0, v4
	s_cmp_eq_u32 vcc_lo, -1
	s_cbranch_scc1 .Lgb_done2
	s_sleep 1
	s_add_i32 s100, s100, 1
	s_cmp_lt_u32 s100, 0x40000
	s_cbranch_scc1 .Lgb_spin2
.Lgb_done2:
	s_branch .LBB0_361
.LBB0_361:
	s_or_b64 exec, exec, s[2:3]
	s_add_u32 s30, s88, 0xfc00000
	s_addc_u32 s31, s89, 0
	s_add_u32 s2, s88, 0xa00000
	v_readlane_b32 s4, v241, 44
	v_writelane_b32 v240, s2, 5
	s_addc_u32 s2, s89, 0
	v_readlane_b32 s5, v241, 45
	v_writelane_b32 v240, s2, 6
	s_mov_b64 s[2:3], -1
	s_and_b64 vcc, exec, s[4:5]
	s_waitcnt lgkmcnt(0)
	s_barrier
	s_cbranch_vccz .LBB0_452
	s_cmpk_gt_i32 s84, 0xbf
	s_cbranch_scc1 .LBB0_451
	s_add_u32 s33, s88, 0x2380c00
	s_mov_b32 s8, 0x3f803f80
	s_addc_u32 s34, s89, 0
	s_movk_i32 s35, 0x67f
	v_mov_b32_e32 v71, 0
	s_mov_b32 s7, 0
	s_add_i32 s58, 0, 0x8900
	s_movk_i32 s59, 0x110
	s_add_i32 s60, 0, 0xf400
	s_add_i32 s61, 0, 0x13800
	s_mov_b32 s9, s8
	s_mov_b32 s10, s8
	s_mov_b32 s11, s8
	s_movk_i32 s68, 0x2600
	s_movk_i32 s69, 0x90
	s_add_i32 s70, 0, 0x14800
	v_mov_b32_e32 v1, 0x2200
	s_mov_b32 s71, s84
	s_branch .LBB0_365

; __device__ __forceinline__ unsigned xb_ld(unsigned* p)              { return __hip_atomic_load(p, __ATOMIC_RELAXED, __HIP_MEMORY_SCOPE_AGENT); }
; __device__ __forceinline__ unsigned xb_add(unsigned* p, unsigned v) { return __hip_atomic_fetch_add(p, v, __ATOMIC_RELAXED, __HIP_MEMORY_SCOPE_AGENT); }
; #define XB_SPIN(cond, bar) do { unsigned _sp = 0; while (cond) { __builtin_amdgcn_s_sleep(1); \
;     if ((++_sp & 255u) == 0u) { if (xb_ld(&(bar)[XB_TMO])) break; if (_sp > XB_SPIN_CAP) { atomicAdd(&(bar)[XB_TMO], 1u); break; } } } } while (0)
; __device__ __forceinline__ void xcd_barrier(const XcdBarrier& b) {
;     asm volatile("s_waitcnt vmcnt(0)" ::: "memory");
;     __syncthreads();
;     if (threadIdx.x == 0) {
;         unsigned* bar = b.bar;
;         __builtin_amdgcn_s_waitcnt(0);
;         unsigned nloc = b.st[0], nx = b.st[1];
;         if (nloc == 0u) { xcd_barrier_complete(bar, b.x, nloc, nx); b.st[0] = nloc; b.st[1] = nx; }
;         const unsigned old = xb_add(&bar[XB_XSUB(b.x)], 1u);
;         const unsigned gen = old / nloc;
;         asm volatile("buffer_inv sc1" ::: "memory");
;         if (old + 1u == (gen + 1u) * nloc) {
;             __builtin_amdgcn_fence(__ATOMIC_RELEASE, "agent");
;             asm volatile("s_waitcnt vmcnt(0)" ::: "memory");
;             const unsigned og = xb_add(&bar[XB_TOP], 1u);
;             const unsigned tg = og / nx;
;             if (og + 1u == (tg + 1u) * nx) xb_add(&bar[XB_TOPGEN], 1u);
;             else XB_SPIN(xb_ld(&bar[XB_TOPGEN]) == tg, bar);
;             asm volatile("" ::: "memory");
;             xb_add(&bar[XB_XGEN(b.x)], 1u);
;             asm volatile("s_waitcnt vmcnt(0)" ::: "memory");
;         } else {
;             XB_SPIN(xb_ld(&bar[XB_XGEN(b.x)]) == gen, bar);
;             asm volatile("" ::: "memory");
;             asm volatile("s_waitcnt vmcnt(0)" ::: "memory");
;         }
;     }
;     __syncthreads();
.LBB0_541:
	s_waitcnt vmcnt(0)
	s_barrier
	s_mov_b64 s[2:3], exec
	v_readlane_b32 s4, v241, 34
	v_readlane_b32 s5, v241, 35
	s_and_b64 s[4:5], s[2:3], s[4:5]
	v_readlane_b32 s82, v241, 50
	v_readlane_b32 s83, v241, 51
	s_mov_b64 exec, s[4:5]
	s_cbranch_execz .LBB0_593
	s_waitcnt vmcnt(0) lgkmcnt(0)
	s_and_b32 s100, s98, -4
	v_mov_b32_e32 v1, s100
	v_mov_b32_e32 v2, 1
	s_bitcmp0_b32 s98, 0
	s_cbranch_scc1 .Lgb_co3
	buffer_wbl2 sc1
	s_waitcnt vmcnt(0)
	global_store_dword v1, v2, s[88:89] offset:3072 sc1
	s_branch .Lgb_inv3
.Lgb_co3:
	global_store_dword v1, v2, s[88:89] offset:3072

; template <int PH> __device__ __forceinline__ void run_phase(Frame& F, const Args& args) {
;     ...
;         mix::MixBufs MB;
;         MB.PROJ = F.PROJ;
;         MB.Eg = (bf16*)(ws + WS_R1);
;         MB.xcm = (bf16*)F.out; MB.vm = MB.xcm + (size_t)M * 512;
;         MB.dlast = (float*)(ws + WS_SMALL); MB.li = (float*)(ws + WS_SMALL + 256 * 1024); MB.fcum = (float*)(ws + WS_SMALL + 512 * 1024); MB.wgt = (float*)(ws + WS_SMALL + 1536 * 1024);
;         MB.flast = (float*)(ws + WS_SMALL + 768 * 1024); MB.mloc = (float*)(ws + WS_SMALL + 772 * 1024);
;         MB.WcmT = F.Wif_t; MB.Lg = (float*)(ws + WS_GSEG); MB.Lm = (float*)(ws + WS_W1); MB.nL = (float*)(ws + WS_W1 + 8 * MiB);
;         MB.A_a = F.A_a; MB.A_b = F.A_b;
;         MB.w_a_up = args.in[3]; MB.b_a_up = args.in[4]; MB.g_gla_norm = args.in[5]; MB.conv_w = args.in[6]; MB.conv_b = args.in[7]; MB.w_q = args.in[8]; MB.w_k = args.in[9]; MB.w_v = args.in[10];
;         MB.b_if = args.in[12]; MB.ml_skip = args.in[13]; MB.g_ml_norm = args.in[14];
;     ...
;         if (IN(4)) {
;             for (int u = F.vcu; u < 256; u += F.G) { const int ty = (u >> 4) & 1, r = ((u >> 5) << 4) | (u & 15), b = r >> 4, h = (r >> 2) & 3, sg = r & 3;
;                 if (ty == 0) mix::gla_unit<true>(F.lds, MB, b, h, sg, F.tid); else mix::ml_out_unit(F.lds, MB, b, h, sg, F.tid); }
.Lgb_spin3:
	global_load_dword v4, v3, s[88:89] offset:3072 sc1
	s_waitcnt vmcnt(0)
	v_cmp_ne_u32_e32 vcc, 0, v4
	s_cmp_eq_u32 vcc_lo, -1
	s_cbranch_scc1 .Lgb_done3
	s_sleep 1
	s_add_i32 s100, s100, 1
	s_cmp_lt_u32 s100, 0x40000
	s_cbranch_scc1 .Lgb_spin3
.Lgb_done3:
	s_branch .LBB0_593
.LBB0_593:
	v_writelane_b32 v240, s93, 7
	v_writelane_b32 v240, s97, 8
	v_writelane_b32 v240, s86, 9
	s_nop 1
	v_writelane_b32 v240, s87, 10
	v_writelane_b32 v240, s92, 11
	s_nop 1
	v_writelane_b32 v240, s93, 12
	v_writelane_b32 v240, s96, 13
	s_or_b64 exec, exec, s[2:3]
	s_add_u32 s2, s88, 0xdc00000
	s_addc_u32 s3, s89, 0
	v_writelane_b32 v240, s2, 14
	s_andn2_b64 vcc, exec, s[12:13]
	s_waitcnt lgkmcnt(0)
	v_writelane_b32 v240, s3, 15
	s_barrier
	s_cbranch_vccnz .LBB0_870
	v_readlane_b32 s4, v241, 18
	v_readlane_b32 s18, v241, 32
	v_readlane_b32 s19, v241, 33
	s_add_u32 s2, s18, 0x1010000
	s_addc_u32 s3, s19, 0
	v_writelane_b32 v240, s2, 16
	v_readlane_b32 s9, v241, 23
	s_mov_b32 s84, 0x3f803f80
	v_writelane_b32 v240, s3, 17
	s_add_i32 s2, 0, 0x22600
	v_writelane_b32 v240, s2, 18
	s_add_i32 s2, 0, 0x22500
	v_mbcnt_lo_u32_b32 v2, -1, 0
	v_readlane_b32 s72, v241, 52
	s_mov_b32 s9, 0
	s_movk_i32 s69, 0x80
	v_mov_b32_e32 v3, 0
	s_movk_i32 s93, 0x67f
	s_movk_i32 s74, 0x1000
	s_movk_i32 s75, 0x110
	v_writelane_b32 v240, s2, 19
	s_add_i32 s2, 0, 0x22400
	s_add_i32 s31, 0, 0x23600
	s_add_i32 s92, 0, 0x23e00
	s_movk_i32 s30, 0x440
	s_mov_b32 s96, 0x19800
	s_mov_b32 s85, s84
	s_mov_b32 s86, s84
	s_mov_b32 s87, s84
	s_mov_b32 s97, 0x22200
	s_movk_i32 s33, 0x2600
	s_mov_b32 s68, 0xf800000
	v_mov_b32_e32 v1, 0x260
	v_mov_b32_e32 v182, 0x358637bd
	s_add_i32 s70, 0, 0x14800
	v_mbcnt_hi_u32_b32 v183, -1, v2
	s_mov_b32 s71, s72
	v_readlane_b32 s5, v241, 19
	v_readlane_b32 s6, v241, 20
	v_readlane_b32 s7, v241, 21
	v_readlane_b32 s8, v241, 22
	v_readlane_b32 s10, v241, 24
	v_readlane_b32 s11, v241, 25
	v_readlane_b32 s12, v241, 26
	v_readlane_b32 s13, v241, 27
	v_readlane_b32 s14, v241, 28
	v_readlane_b32 s15, v241, 29
	v_readlane_b32 s16, v241, 30
	v_readlane_b32 s17, v241, 31
	v_writelane_b32 v240, s2, 20
	s_branch .LBB0_596

; __device__ __forceinline__ unsigned xb_ld(unsigned* p)              { return __hip_atomic_load(p, __ATOMIC_RELAXED, __HIP_MEMORY_SCOPE_AGENT); }
; __device__ __forceinline__ unsigned xb_add(unsigned* p, unsigned v) { return __hip_atomic_fetch_add(p, v, __ATOMIC_RELAXED, __HIP_MEMORY_SCOPE_AGENT); }
; #define XB_SPIN(cond, bar) do { unsigned _sp = 0; while (cond) { __builtin_amdgcn_s_sleep(1); \
;     if ((++_sp & 255u) == 0u) { if (xb_ld(&(bar)[XB_TMO])) break; if (_sp > XB_SPIN_CAP) { atomicAdd(&(bar)[XB_TMO], 1u); break; } } } } while (0)
; __device__ __forceinline__ void xcd_barrier(const XcdBarrier& b) {
;     asm volatile("s_waitcnt vmcnt(0)" ::: "memory");
;     __syncthreads();
;     if (threadIdx.x == 0) {
;         unsigned* bar = b.bar;
;         __builtin_amdgcn_s_waitcnt(0);
;         unsigned nloc = b.st[0], nx = b.st[1];
;         if (nloc == 0u) { xcd_barrier_complete(bar, b.x, nloc, nx); b.st[0] = nloc; b.st[1] = nx; }
;         const unsigned old = xb_add(&bar[XB_XSUB(b.x)], 1u);
;         const unsigned gen = old / nloc;
;         asm volatile("buffer_inv sc1" ::: "memory");
;         if (old + 1u == (gen + 1u) * nloc) {
;             __builtin_amdgcn_fence(__ATOMIC_RELEASE, "agent");
;             asm volatile("s_waitcnt vmcnt(0)" ::: "memory");
;             const unsigned og = xb_add(&bar[XB_TOP], 1u);
;             const unsigned tg = og / nx;
;             if (og + 1u == (tg + 1u) * nx) xb_add(&bar[XB_TOPGEN], 1u);
;             else XB_SPIN(xb_ld(&bar[XB_TOPGEN]) == tg, bar);
;             asm volatile("" ::: "memory");
;             xb_add(&bar[XB_XGEN(b.x)], 1u);
;             asm volatile("s_waitcnt vmcnt(0)" ::: "memory");
;         } else {
;             XB_SPIN(xb_ld(&bar[XB_XGEN(b.x)]) == gen, bar);
;             asm volatile("" ::: "memory");
;             asm volatile("s_waitcnt vmcnt(0)" ::: "memory");
;         }
;     }
;     __syncthreads();
.LBB0_1103:
	s_waitcnt vmcnt(0)
	s_barrier
	s_mov_b64 s[2:3], exec
	v_readlane_b32 s4, v241, 34
	v_readlane_b32 s5, v241, 35
	s_and_b64 s[4:5], s[2:3], s[4:5]
	s_mov_b64 exec, s[4:5]
	s_cbranch_execz .LBB0_1155
	s_waitcnt vmcnt(0) lgkmcnt(0)
	s_and_b32 s100, s98, -4
	s_addk_i32 s100, 0x1000
	v_mov_b32_e32 v1, s100
	v_mov_b32_e32 v2, 1
	s_bitcmp0_b32 s98, 0
	s_cbranch_scc1 .Lgb_co5
	buffer_wbl2 sc1
	s_waitcnt vmcnt(0)
	global_store_dword v1, v2, s[88:89] offset:1024 sc1
	s_branch .Lgb_inv5

; __device__ __forceinline__ unsigned xb_ld(unsigned* p)              { return __hip_atomic_load(p, __ATOMIC_RELAXED, __HIP_MEMORY_SCOPE_AGENT); }
; __device__ __forceinline__ unsigned xb_add(unsigned* p, unsigned v) { return __hip_atomic_fetch_add(p, v, __ATOMIC_RELAXED, __HIP_MEMORY_SCOPE_AGENT); }
; #define XB_SPIN(cond, bar) do { unsigned _sp = 0; while (cond) { __builtin_amdgcn_s_sleep(1); \
;     if ((++_sp & 255u) == 0u) { if (xb_ld(&(bar)[XB_TMO])) break; if (_sp > XB_SPIN_CAP) { atomicAdd(&(bar)[XB_TMO], 1u); break; } } } } while (0)
; __device__ __forceinline__ void xcd_barrier(const XcdBarrier& b) {
;     asm volatile("s_waitcnt vmcnt(0)" ::: "memory");
;     __syncthreads();
;     if (threadIdx.x == 0) {
;         unsigned* bar = b.bar;
;         __builtin_amdgcn_s_waitcnt(0);
;         unsigned nloc = b.st[0], nx = b.st[1];
;         if (nloc == 0u) { xcd_barrier_complete(bar, b.x, nloc, nx); b.st[0] = nloc; b.st[1] = nx; }
;         const unsigned old = xb_add(&bar[XB_XSUB(b.x)], 1u);
;         const unsigned gen = old / nloc;
;         asm volatile("buffer_inv sc1" ::: "memory");
;         if (old + 1u == (gen + 1u) * nloc) {
;             __builtin_amdgcn_fence(__ATOMIC_RELEASE, "agent");
;             asm volatile("s_waitcnt vmcnt(0)" ::: "memory");
;             const unsigned og = xb_add(&bar[XB_TOP], 1u);
;             const unsigned tg = og / nx;
;             if (og + 1u == (tg + 1u) * nx) xb_add(&bar[XB_TOPGEN], 1u);
;             else XB_SPIN(xb_ld(&bar[XB_TOPGEN]) == tg, bar);
;             asm volatile("" ::: "memory");
;             xb_add(&bar[XB_XGEN(b.x)], 1u);
;             asm volatile("s_waitcnt vmcnt(0)" ::: "memory");
;         } else {
;             XB_SPIN(xb_ld(&bar[XB_XGEN(b.x)]) == gen, bar);
;             asm volatile("" ::: "memory");
;             asm volatile("s_waitcnt vmcnt(0)" ::: "memory");
;         }
;     }
;     __syncthreads();
.Lgb_inv5:
	buffer_inv sc1
	s_mov_b32 exec_lo, -1
	s_mov_b32 exec_hi, 0
	v_mbcnt_lo_u32_b32 v3, -1, 0
	v_lshl_add_u32 v3, v3, 2, s99
	v_add_u32_e32 v3, 0x1000, v3
	s_mov_b32 s100, 0

; #define GAS __attribute__((address_space(1)))
; #define VM_WAIT() asm volatile("s_waitcnt vmcnt(0)" ::: "memory")
; __device__ __forceinline__ void nan_rows_f32(Frame& F, float* out) {
;     int tx_ = (int)threadIdx.x; asm volatile("" : "+v"(tx_)); const int lane = tx_ & 63;
;     const int gw = F.vcu * NWAVES + F.wave, NGW = F.G * NWAVES; const float q = __builtin_nanf("");
;     for (int m = gw; m < M; m += NGW) { GAS f32x4* o = (GAS f32x4*)(out + (size_t)m * D) + lane;
; #pragma unroll
;         for (int j = 0; j < 4; ++j) o[64 * j] = (f32x4){q, q, q, q}; }
; template <int PH> __device__ __forceinline__ void run_phase(Frame& F, const Args& args) {
;     ...
;     if (IN(6)) {
;         unsigned poison = (__hip_atomic_load(F.ctl + CW_TMO, RLX_AGENT) != 0u);
;         if (F.G != 256) { nan_rows_f32(F, F.out); wrong_grid_word(F); VM_WAIT(); __syncthreads(); }
.Lgb_done5:
	s_branch .LBB0_1155
.LBB0_1155:
	s_or_b64 exec, exec, s[2:3]
	s_waitcnt lgkmcnt(0)
	v_mov_b32_e32 v1, 0
	s_barrier
	global_load_dword v213, v1, s[88:89] sc1
	v_readlane_b32 s4, v241, 44
	v_readlane_b32 s5, v241, 45
	s_add_u32 s12, s88, 0xc400000
	s_addc_u32 s13, s89, 0
	v_cndmask_b32_e64 v1, 0, 1, s[4:5]
	v_cmp_ne_u32_e64 s[2:3], 1, v1
	s_andn2_b64 vcc, exec, s[4:5]
	s_mov_b64 s[4:5], -1
	s_cbranch_vccnz .LBB0_1162
	v_mov_b32_e32 v1, v0
	s_cmpk_gt_i32 s70, 0x3fff
	s_cbranch_scc1 .LBB0_1159
	v_readlane_b32 s16, v241, 18
	v_readlane_b32 s17, v241, 19
	v_readlane_b32 s18, v241, 20
	v_readlane_b32 s19, v241, 21
	v_readlane_b32 s28, v241, 30
	v_readlane_b32 s29, v241, 31
	s_ashr_i32 s71, s70, 31
	v_readlane_b32 s30, v241, 32
	v_readlane_b32 s31, v241, 33
	s_mov_b64 s[16:17], s[28:29]
	s_lshl_b64 s[4:5], s[70:71], 12
	s_mov_b64 s[18:19], s[30:31]
	v_and_b32_e32 v1, 63, v1
	s_add_u32 s4, s18, s4
	s_mov_b32 s8, 0x7fc00000
	v_lshlrev_b32_e32 v2, 4, v1
	v_mov_b32_e32 v3, 0
	s_addc_u32 s5, s19, s5
	s_mov_b32 s9, s8
	v_lshl_add_u64 v[2:3], s[4:5], 0, v[2:3]
	s_mov_b64 s[4:5], 0xc00
	s_ashr_i32 s73, s72, 31
	s_mov_b32 s10, s8
	s_mov_b32 s11, s8
	v_mov_b64_e32 v[4:5], s[8:9]
	v_lshl_add_u64 v[2:3], v[2:3], 0, s[4:5]
	s_lshl_b64 s[4:5], s[72:73], 12
	v_mov_b64_e32 v[6:7], s[10:11]
	s_mov_b32 s6, s70
	v_readlane_b32 s20, v241, 22
	v_readlane_b32 s21, v241, 23
	v_readlane_b32 s22, v241, 24
	v_readlane_b32 s23, v241, 25
	v_readlane_b32 s24, v241, 26
	v_readlane_b32 s25, v241, 27
	v_readlane_b32 s26, v241, 28
	v_readlane_b32 s27, v241, 29

; __device__ __forceinline__ unsigned xb_ld(unsigned* p)              { return __hip_atomic_load(p, __ATOMIC_RELAXED, __HIP_MEMORY_SCOPE_AGENT); }
; __device__ __forceinline__ unsigned xb_add(unsigned* p, unsigned v) { return __hip_atomic_fetch_add(p, v, __ATOMIC_RELAXED, __HIP_MEMORY_SCOPE_AGENT); }
; #define XB_SPIN(cond, bar) do { unsigned _sp = 0; while (cond) { __builtin_amdgcn_s_sleep(1); \
;     if ((++_sp & 255u) == 0u) { if (xb_ld(&(bar)[XB_TMO])) break; if (_sp > XB_SPIN_CAP) { atomicAdd(&(bar)[XB_TMO], 1u); break; } } } } while (0)
; __device__ __forceinline__ void xcd_barrier(const XcdBarrier& b) {
;     asm volatile("s_waitcnt vmcnt(0)" ::: "memory");
;     __syncthreads();
;     if (threadIdx.x == 0) {
;         unsigned* bar = b.bar;
;         __builtin_amdgcn_s_waitcnt(0);
;         unsigned nloc = b.st[0], nx = b.st[1];
;         if (nloc == 0u) { xcd_barrier_complete(bar, b.x, nloc, nx); b.st[0] = nloc; b.st[1] = nx; }
;         const unsigned old = xb_add(&bar[XB_XSUB(b.x)], 1u);
;         const unsigned gen = old / nloc;
;         asm volatile("buffer_inv sc1" ::: "memory");
;         if (old + 1u == (gen + 1u) * nloc) {
;             __builtin_amdgcn_fence(__ATOMIC_RELEASE, "agent");
;             asm volatile("s_waitcnt vmcnt(0)" ::: "memory");
;             const unsigned og = xb_add(&bar[XB_TOP], 1u);
;             const unsigned tg = og / nx;
;             if (og + 1u == (tg + 1u) * nx) xb_add(&bar[XB_TOPGEN], 1u);
;             else XB_SPIN(xb_ld(&bar[XB_TOPGEN]) == tg, bar);
;             asm volatile("" ::: "memory");
;             xb_add(&bar[XB_XGEN(b.x)], 1u);
;             asm volatile("s_waitcnt vmcnt(0)" ::: "memory");
;         } else {
;             XB_SPIN(xb_ld(&bar[XB_XGEN(b.x)]) == gen, bar);
;             asm volatile("" ::: "memory");
;             asm volatile("s_waitcnt vmcnt(0)" ::: "memory");
;         }
;     }
;     __syncthreads();
.LBB0_1242:
	s_waitcnt vmcnt(0)
	s_waitcnt lgkmcnt(0)
	s_barrier
	s_mov_b64 s[0:1], exec
	v_readlane_b32 s6, v241, 34
	v_readlane_b32 s7, v241, 35
	v_readlane_b32 s78, v241, 55
	s_and_b64 s[6:7], s[0:1], s[6:7]
	v_readlane_b32 s79, v241, 56
	s_mov_b64 exec, s[6:7]
	s_cbranch_execz .LBB0_1294
	s_waitcnt vmcnt(0) lgkmcnt(0)
	s_and_b32 s100, s98, -4
	s_addk_i32 s100, 0x1000
	v_mov_b32_e32 v1, s100
	v_mov_b32_e32 v2, 1
	s_bitcmp0_b32 s98, 0
	s_cbranch_scc1 .Lgb_co6
	buffer_wbl2 sc1
	s_waitcnt vmcnt(0)
	global_store_dword v1, v2, s[88:89] offset:2048 sc1
	s_branch .Lgb_inv6

;     __host__ __device__ bool next(int i, Unit& u) const {
;         const long L = (long)i * G + c; if (L >= nwg) return false;
;         int wgid = (int)L; { const int q = nwg / NXCD, r = nwg % NXCD, xcd = wgid % NXCD, off = wgid / NXCD; wgid = (xcd < r ? xcd * (q + 1) : r * (q + 1) + (xcd - r) * q) + off; }
;         const int nig = wgm * nN, gid = wgid / nig, fm = gid * wgm, gsz = (nM - fm) < wgm ? (nM - fm) : wgm;
;         u.pm = fm + ((wgid % nig) % gsz); u.pn = (wgid % nig) / gsz; return true;
; template <int PH> __device__ __forceinline__ void run_phase(Frame& F, const Args& args) {
;     ...
;         pg8::Gemm g{F.XN2, F.Wup_t, M, FF, D}; pg8::StaticOrder S; S.init(M, FF, F.G, (int)blockIdx.x, WGM_P7);
;         pg8::EpiBf16<2> E{F.U, FF};
;         pg8::gemm_phase<pg8::EpiBf16<2>, pg8::StaticOrder, PG8_ALIGN, PG8_SP2>(F.lds + RING_OFF, g, S, E);
.Lgb_done6:
	s_branch .LBB0_1294
.LBB0_1294:
	s_or_b64 exec, exec, s[0:1]
	v_mov_b32_e32 v10, v0
	s_cmpk_lt_i32 s66, 0x400
	s_waitcnt lgkmcnt(0)
	s_barrier
	s_cselect_b64 s[0:1], -1, 0
	s_cmpk_gt_i32 s66, 0x3ff
	v_readfirstlane_b32 s14, v10
	s_cbranch_scc1 .LBB0_1300
	s_ashr_i32 s6, s66, 31
	s_lshr_b32 s6, s6, 29
	s_add_i32 s8, s66, s6
	s_and_b32 s6, s8, -8
	s_sub_i32 s9, s66, s6
	s_cmp_gt_i32 s9, -1
	s_cbranch_scc0 .LBB0_1297
	s_lshl_b32 s10, s9, 7
	s_cbranch_execz .LBB0_1298
	s_branch .LBB0_1299

; __device__ __forceinline__ unsigned xb_ld(unsigned* p)              { return __hip_atomic_load(p, __ATOMIC_RELAXED, __HIP_MEMORY_SCOPE_AGENT); }
; __device__ __forceinline__ unsigned xb_add(unsigned* p, unsigned v) { return __hip_atomic_fetch_add(p, v, __ATOMIC_RELAXED, __HIP_MEMORY_SCOPE_AGENT); }
; #define XB_SPIN(cond, bar) do { unsigned _sp = 0; while (cond) { __builtin_amdgcn_s_sleep(1); \
;     if ((++_sp & 255u) == 0u) { if (xb_ld(&(bar)[XB_TMO])) break; if (_sp > XB_SPIN_CAP) { atomicAdd(&(bar)[XB_TMO], 1u); break; } } } } while (0)
; __device__ __forceinline__ void xcd_barrier(const XcdBarrier& b) {
;     asm volatile("s_waitcnt vmcnt(0)" ::: "memory");
;     __syncthreads();
;     if (threadIdx.x == 0) {
;         unsigned* bar = b.bar;
;         __builtin_amdgcn_s_waitcnt(0);
;         unsigned nloc = b.st[0], nx = b.st[1];
;         if (nloc == 0u) { xcd_barrier_complete(bar, b.x, nloc, nx); b.st[0] = nloc; b.st[1] = nx; }
;         const unsigned old = xb_add(&bar[XB_XSUB(b.x)], 1u);
;         const unsigned gen = old / nloc;
;         asm volatile("buffer_inv sc1" ::: "memory");
;         if (old + 1u == (gen + 1u) * nloc) {
;             __builtin_amdgcn_fence(__ATOMIC_RELEASE, "agent");
;             asm volatile("s_waitcnt vmcnt(0)" ::: "memory");
;             const unsigned og = xb_add(&bar[XB_TOP], 1u);
;             const unsigned tg = og / nx;
;             if (og + 1u == (tg + 1u) * nx) xb_add(&bar[XB_TOPGEN], 1u);
;             else XB_SPIN(xb_ld(&bar[XB_TOPGEN]) == tg, bar);
;             asm volatile("" ::: "memory");
;             xb_add(&bar[XB_XGEN(b.x)], 1u);
;             asm volatile("s_waitcnt vmcnt(0)" ::: "memory");
;         } else {
;             XB_SPIN(xb_ld(&bar[XB_XGEN(b.x)]) == gen, bar);
;             asm volatile("" ::: "memory");
;             asm volatile("s_waitcnt vmcnt(0)" ::: "memory");
;         }
;     }
;     __syncthreads();
.LBB0_1352:
	s_waitcnt vmcnt(0)
	s_waitcnt vmcnt(0)
	s_barrier
	s_mov_b64 s[0:1], exec
	v_readlane_b32 s6, v241, 34
	v_readlane_b32 s7, v241, 35
	s_and_b64 s[6:7], s[0:1], s[6:7]
	s_mov_b64 exec, s[6:7]
	s_cbranch_execz .LBB0_1404
	s_waitcnt vmcnt(0) lgkmcnt(0)
	s_and_b32 s100, s98, -4
	s_addk_i32 s100, 0x1000
	v_mov_b32_e32 v1, s100
	v_mov_b32_e32 v2, 1
	s_bitcmp0_b32 s98, 0
	s_cbranch_scc1 .Lgb_co7
	buffer_wbl2 sc1
	s_waitcnt vmcnt(0)
	global_store_dword v1, v2, s[88:89] offset:3072 sc1
	s_branch .Lgb_inv7

; #define GAS __attribute__((address_space(1)))
; __device__ __forceinline__ void nan_rows_f32(Frame& F, float* out) {
;     int tx_ = (int)threadIdx.x; asm volatile("" : "+v"(tx_)); const int lane = tx_ & 63;
;     const int gw = F.vcu * NWAVES + F.wave, NGW = F.G * NWAVES; const float q = __builtin_nanf("");
;     for (int m = gw; m < M; m += NGW) { GAS f32x4* o = (GAS f32x4*)(out + (size_t)m * D) + lane;
; #pragma unroll
;         for (int j = 0; j < 4; ++j) o[64 * j] = (f32x4){q, q, q, q}; }
; template <int PH> __device__ __forceinline__ void run_phase(Frame& F, const Args& args) {
;     ...
;     if (IN(8)) {
;         unsigned poison = (__hip_atomic_load(F.ctl + CW_TMO, RLX_AGENT) != 0u);
;         poison |= __hip_atomic_load((gu32*)((const unsigned*)(F.ctl + CW_BAR) + XB_TMO), RLX_AGENT) != 0u;
;         if (F.G != 256) { nan_rows_f32(F, F.out); wrong_grid_word(F); }
.Lgb_done7:
	s_branch .LBB0_1404
.LBB0_1404:
	s_or_b64 exec, exec, s[0:1]
	s_waitcnt lgkmcnt(0)
	v_mov_b32_e32 v1, 0
	s_barrier
	global_load_dword v214, v1, s[88:89] sc1
	v_mov_b32_e32 v1, 0x4000
	global_load_dword v215, v1, s[88:89] offset:512 sc1
	s_and_b64 vcc, exec, s[2:3]
	s_mov_b64 s[0:1], -1
	s_cbranch_vccnz .LBB0_1411
	v_mov_b32_e32 v1, v0
	s_cmpk_gt_i32 s70, 0x3fff
	s_cbranch_scc1 .LBB0_1408
	v_readlane_b32 s16, v241, 18
	v_readlane_b32 s17, v241, 19
	v_readlane_b32 s18, v241, 20
	v_readlane_b32 s19, v241, 21
	v_readlane_b32 s28, v241, 30
	v_readlane_b32 s29, v241, 31
	s_ashr_i32 s71, s70, 31
	v_readlane_b32 s30, v241, 32
	v_readlane_b32 s31, v241, 33
	s_mov_b64 s[16:17], s[28:29]
	s_lshl_b64 s[0:1], s[70:71], 12
	s_mov_b64 s[18:19], s[30:31]
	v_and_b32_e32 v1, 63, v1
	s_add_u32 s0, s18, s0
	s_mov_b32 s8, 0x7fc00000
	v_lshlrev_b32_e32 v2, 4, v1
	v_mov_b32_e32 v3, 0
	s_addc_u32 s1, s19, s1
	s_mov_b32 s9, s8
	v_lshl_add_u64 v[2:3], s[0:1], 0, v[2:3]
	s_mov_b64 s[0:1], 0xc00
	s_ashr_i32 s73, s72, 31
	s_mov_b32 s10, s8
	s_mov_b32 s11, s8
	v_mov_b64_e32 v[4:5], s[8:9]
	v_lshl_add_u64 v[2:3], v[2:3], 0, s[0:1]
	s_lshl_b64 s[0:1], s[72:73], 12
	v_mov_b64_e32 v[6:7], s[10:11]
	v_readlane_b32 s20, v241, 22
	v_readlane_b32 s21, v241, 23
	v_readlane_b32 s22, v241, 24
	v_readlane_b32 s23, v241, 25
	v_readlane_b32 s24, v241, 26
	v_readlane_b32 s25, v241, 27
	v_readlane_b32 s26, v241, 28
	v_readlane_b32 s27, v241, 29
